# in-proj: memory K / V^T units moved from workgroups 240-243 (2 GEMM switches) to workgroups 0-3 (1 switch); their weight-conversion shares swapped
# speedup vs baseline: 1.0077x; 1.0077x over previous
.LBB0_18:
	s_cmpk_lg_i32 s52, 0x100
	s_load_dwordx16 s[36:51], s[0:1], 0x0
	s_load_dwordx8 s[20:27], s[0:1], 0x40
	s_cselect_b64 s[0:1], -1, 0
	v_writelane_b32 v238, s0, 2
	s_cmpk_lt_i32 s2, 0x100
	s_mov_b32 s16, s2
	v_writelane_b32 v238, s1, 3
	s_cselect_b64 s[0:1], -1, 0
	v_writelane_b32 v238, s0, 4
	s_ashr_i32 s17, s2, 31
	s_ashr_i32 s97, s52, 31
	v_writelane_b32 v238, s1, 5
	s_lshr_b32 s0, s17, 29
	s_add_i32 s0, s2, s0
	s_ashr_i32 s7, s0, 3
	s_and_b32 s0, s0, -8
	s_sub_i32 s9, s2, s0
	s_lshl_b32 s8, s9, 5
	s_waitcnt lgkmcnt(0)
	s_cmp_eq_u64 s[36:37], 0
	s_cselect_b64 s[0:1], -1, 0
	v_writelane_b32 v238, s0, 6
	s_mul_i32 s6, s53, s52
	s_mov_b32 s96, s52
	v_writelane_b32 v238, s1, 7
	v_writelane_b32 v238, s20, 8
	s_cmp_eq_u64 s[26:27], 0
	s_cselect_b64 s[0:1], -1, 0
	v_writelane_b32 v238, s21, 9
	v_writelane_b32 v238, s22, 10
	v_writelane_b32 v238, s23, 11
	v_writelane_b32 v238, s24, 12
	v_writelane_b32 v238, s25, 13
	v_writelane_b32 v238, s26, 14
	v_writelane_b32 v238, s27, 15
	v_writelane_b32 v238, s0, 16
	s_cmpk_lt_i32 s2, 0x200
	v_mbcnt_lo_u32_b32 v0, -1, 0
	v_writelane_b32 v238, s1, 17
	s_cselect_b64 s[0:1], -1, 0
	v_writelane_b32 v238, s0, 18
	s_mov_b32 s10, 0
	v_mov_b32_e32 v1, 0
	v_writelane_b32 v238, s1, 19
	s_add_i32 s0, s2, 0x100
	s_and_b32 s1, s2, 3
	s_lshl_b32 s2, s2, 4
	v_writelane_b32 v238, s2, 20
	s_andn2_b32 s2, s2, 63
	s_ashr_i32 s3, s2, 31
	v_writelane_b32 v238, s2, 21
	v_mov_b32_e32 v205, 1
	v_mov_b32_e32 v206, 0x3727c5ac
	v_writelane_b32 v238, s3, 22
	s_lshl_b32 s2, s1, 6
	v_writelane_b32 v238, s2, 23
	s_lshl_b64 s[2:3], s[16:17], 14
	v_writelane_b32 v238, s2, 24
	s_lshl_b32 s1, s1, 7
	v_mov_b32_e32 v207, 0x260
	v_writelane_b32 v238, s3, 25
	v_writelane_b32 v238, s1, 26
	s_bitset1_b32 s1, 10
	v_writelane_b32 v238, s1, 27
	s_lshl_b32 s1, s0, 4
	s_and_b32 s2, s1, 0xffffffc0
	s_ashr_i32 s3, s2, 31
	v_writelane_b32 v238, s2, 28
	s_ashr_i32 s1, s0, 31
	s_lshl_b64 s[0:1], s[0:1], 14
	v_writelane_b32 v238, s3, 29
	v_writelane_b32 v238, s0, 30
	s_cmp_ge_i32 s16, s10
	v_mov_b32_e32 v208, 0x358637bd
	v_writelane_b32 v238, s1, 31
	s_cselect_b64 s[0:1], -1, 0
	s_mov_b32 s11, 2
	s_cmp_lt_i32 s16, s11
	s_cselect_b64 s[2:3], -1, 0
	s_and_b64 s[0:1], s[0:1], s[2:3]
	s_sub_i32 s2, s16, s10
	s_and_b64 s[0:1], s[0:1], exec
	s_cselect_b32 s0, s2, 0x1000000
	v_writelane_b32 v238, s0, 32
	s_not_b32 s0, s16
	s_add_i32 s0, s52, s0
	s_cmp_ge_i32 s16, s11
	v_writelane_b32 v238, s0, 33
	s_cselect_b64 s[0:1], -1, 0
	s_mov_b32 s2, 4
	s_cmp_lt_i32 s16, s2
	s_cselect_b64 s[2:3], -1, 0
	s_and_b64 s[0:1], s[0:1], s[2:3]
	s_sub_i32 s2, s16, s11
	s_and_b64 s[0:1], s[0:1], exec
	s_cselect_b32 s0, s2, 0x1000000
	v_writelane_b32 v238, s0, 34
	s_add_i32 s0, s16, 0xffffff60
	s_add_i32 s1, s16, 0xffffffa0
	s_cmpk_lt_u32 s0, 0x50
	s_cselect_b32 s0, s1, -1
	s_cmp_lt_i32 s16, 64
	s_cselect_b32 s2, s16, s0
	s_cmp_lt_i32 s16, 4
	s_cselect_b32 s2, -1, s2
	s_add_i32 s0, s16, 0xffffff10
	s_cmp_lt_u32 s0, 4
	s_cselect_b32 s2, s0, s2
	s_lshl_b32 s60, s52, 3
	s_cmpk_eq_i32 s52, 0x100
	s_cselect_b64 s[0:1], -1, 0
	s_and_b64 s[10:11], s[0:1], exec
	s_cselect_b32 s10, s2, s16
	s_cselect_b32 s29, 0x480, s60
	s_cmp_lt_i32 s10, 0
	s_cselect_b64 s[18:19], -1, 0
	s_mov_b32 s3, 0
	s_mov_b32 s2, s16
	v_writelane_b32 v238, s18, 35
	s_mov_b32 s53, s3
	s_lshl_b32 s15, s10, 3
	v_writelane_b32 v238, s19, 36
	s_lshl_b64 s[18:19], s[2:3], 9
	s_lshl_b32 s62, s16, 3
	v_writelane_b32 v238, s18, 37
	s_lshl_b64 s[92:93], s[52:53], 9
	v_mov_b64_e32 v[186:187], 0x100
	v_writelane_b32 v238, s19, 38
	s_add_u32 s18, s84, 0x1aa00200
	s_addc_u32 s19, s85, 0
	v_writelane_b32 v238, s18, 39
	v_mov_b64_e32 v[188:189], 0xff
	v_mbcnt_hi_u32_b32 v209, -1, v0
	v_writelane_b32 v238, s19, 40
	s_add_u32 s18, s84, 0x1aa00400
	s_addc_u32 s19, s85, 0
	v_writelane_b32 v238, s18, 41
	v_mov_b32_e32 v210, 2
	v_mov_b32_e32 v211, 4
	v_writelane_b32 v238, s19, 42
	s_add_u32 s18, s84, 0x1aa00500
	s_addc_u32 s19, s85, 0
	v_writelane_b32 v238, s18, 43
	v_mov_b32_e32 v212, 3
	v_mov_b32_e32 v213, 0x41b17218
	v_writelane_b32 v238, s19, 44
	s_add_u32 s18, s84, 0x1aa00600
	s_addc_u32 s19, s85, 0
	v_writelane_b32 v238, s18, 45
	v_mov_b32_e32 v214, 0x9800000
	v_mov_b32_e32 v215, 0x9000000
	v_writelane_b32 v238, s19, 46
	s_add_u32 s18, s84, 0x1aa00700
	s_addc_u32 s19, s85, 0
	v_writelane_b32 v238, s18, 47
	s_movk_i32 s59, 0x2a00
	s_mov_b32 s89, 0x800000
	v_writelane_b32 v238, s19, 48
	s_add_u32 s18, s84, 0x1aa00800
	s_addc_u32 s19, s85, 0
	v_writelane_b32 v238, s18, 49
	s_mov_b64 s[20:21], 0x80
	s_mov_b32 s34, 0x3e0293ee
	v_writelane_b32 v238, s19, 50
	s_add_u32 s18, s84, 0x1aa00900
	s_addc_u32 s19, s85, 0
	v_writelane_b32 v238, s18, 51
	s_mov_b32 s88, 0x3f803f80
	s_nop 0
	v_writelane_b32 v238, s19, 52
	s_add_u32 s18, s84, 0x1aa00a00
	s_addc_u32 s19, s85, 0
	v_writelane_b32 v238, s18, 53
	s_nop 1
	v_writelane_b32 v238, s19, 54
	s_add_u32 s18, s84, 0x1aa00b00
	s_addc_u32 s19, s85, 0
	v_writelane_b32 v238, s18, 55
	s_nop 1
	v_writelane_b32 v238, s19, 56
	s_add_u32 s18, s84, 0x1aa00c00
	s_addc_u32 s19, s85, 0
	v_writelane_b32 v238, s18, 57
	s_nop 1
	v_writelane_b32 v238, s19, 58
	s_add_u32 s18, s84, 0x1aa00d00
	s_addc_u32 s19, s85, 0
	v_writelane_b32 v238, s18, 59
	s_nop 1
	v_writelane_b32 v238, s19, 60
	s_add_u32 s18, s84, 0x1aa00e00
	s_addc_u32 s19, s85, 0
	v_writelane_b32 v238, s18, 61
	s_nop 1
	v_writelane_b32 v238, s19, 62
	s_add_u32 s18, s84, 0x1aa00f00
	s_addc_u32 s19, s85, 0
	v_writelane_b32 v238, s18, 63
	s_nop 1
	v_writelane_b32 v237, s19, 0
	s_add_u32 s18, s84, 0x1aa01000
	s_addc_u32 s19, s85, 0
	v_writelane_b32 v237, s18, 1
	s_nop 1
	v_writelane_b32 v237, s19, 2
	s_add_u32 s18, s84, 0x1aa01100
	s_addc_u32 s19, s85, 0
	v_writelane_b32 v237, s18, 3
	s_nop 1
	v_writelane_b32 v237, s19, 4
	s_add_u32 s18, s84, 0x1aa01200
	s_addc_u32 s19, s85, 0
	v_writelane_b32 v237, s18, 5
	s_nop 1
	v_writelane_b32 v237, s19, 6
	s_add_u32 s18, s84, 0x1aa01300
	s_addc_u32 s19, s85, 0
	v_writelane_b32 v237, s18, 7
	s_cmp_eq_u32 s13, 15
	s_nop 0
	v_writelane_b32 v237, s19, 8
	s_cselect_b64 s[18:19], -1, 0
	v_writelane_b32 v237, s18, 9
	s_cmp_eq_u32 s13, 14
	s_nop 0
	v_writelane_b32 v237, s19, 10
	s_cselect_b64 s[18:19], -1, 0
	v_writelane_b32 v237, s18, 11
	s_cmp_eq_u32 s13, 13
	s_nop 0
	v_writelane_b32 v237, s19, 12
	s_cselect_b64 s[18:19], -1, 0
	v_writelane_b32 v237, s18, 13
	s_cmp_eq_u32 s13, 12
	s_nop 0
	v_writelane_b32 v237, s19, 14
	s_cselect_b64 s[18:19], -1, 0
	v_writelane_b32 v237, s18, 15
	s_cmp_eq_u32 s13, 11
	s_nop 0
	v_writelane_b32 v237, s19, 16
	s_cselect_b64 s[18:19], -1, 0
	v_writelane_b32 v237, s18, 17
	s_cmp_eq_u32 s13, 10
	s_nop 0
	v_writelane_b32 v237, s19, 18
	s_cselect_b64 s[18:19], -1, 0
	v_writelane_b32 v237, s18, 19
	s_cmp_eq_u32 s13, 9
	s_nop 0
	v_writelane_b32 v237, s19, 20
	s_cselect_b64 s[18:19], -1, 0
	v_writelane_b32 v237, s18, 21
	s_cmp_eq_u32 s13, 8
	s_nop 0
	v_writelane_b32 v237, s19, 22
	s_cselect_b64 s[18:19], -1, 0
	v_writelane_b32 v237, s18, 23
	s_cmp_eq_u32 s13, 7
	s_nop 0
	v_writelane_b32 v237, s19, 24
	s_cselect_b64 s[18:19], -1, 0
	v_writelane_b32 v237, s18, 25
	s_cmp_eq_u32 s13, 6
	s_nop 0
	v_writelane_b32 v237, s19, 26
	s_cselect_b64 s[18:19], -1, 0
	v_writelane_b32 v237, s18, 27
	s_cmp_eq_u32 s13, 5
	s_nop 0
	v_writelane_b32 v237, s19, 28
	s_cselect_b64 s[18:19], -1, 0
	v_writelane_b32 v237, s18, 29
	s_cmp_eq_u32 s13, 4
	s_nop 0
	v_writelane_b32 v237, s19, 30
	s_cselect_b64 s[18:19], -1, 0
	v_writelane_b32 v237, s18, 31
	s_cmp_eq_u32 s13, 3
	s_nop 0
	v_writelane_b32 v237, s19, 32
	s_cselect_b64 s[18:19], -1, 0
	v_writelane_b32 v237, s18, 33
	s_cmp_eq_u32 s13, 2
	s_nop 0
	v_writelane_b32 v237, s19, 34
	s_cselect_b64 s[18:19], -1, 0
	v_writelane_b32 v237, s18, 35
	s_cmp_eq_u32 s13, 1
	s_nop 0
	v_writelane_b32 v237, s19, 36
	s_cselect_b64 s[18:19], -1, 0
	v_writelane_b32 v237, s18, 37
	s_cmp_eq_u32 s13, 0
	s_nop 0
	v_writelane_b32 v237, s19, 38
	s_cselect_b64 s[18:19], -1, 0
	s_lshl_b32 s11, s13, 8
	s_add_u32 s4, s4, s11
	s_addc_u32 s5, s5, 0
	v_writelane_b32 v237, s18, 39
	s_add_u32 s12, s4, 0x1400
	s_addc_u32 s13, s5, 0
	v_writelane_b32 v237, s19, 40
	v_writelane_b32 v237, s12, 41
	s_add_u32 s4, s4, 0x2400
	s_addc_u32 s5, s5, 0
	v_writelane_b32 v237, s13, 42
	v_writelane_b32 v237, s4, 43
	s_nop 1
	v_writelane_b32 v237, s5, 44
	s_add_u32 s4, s84, 0x1aa03400
	s_addc_u32 s5, s85, 0
	v_writelane_b32 v237, s4, 45
	s_nop 1
	v_writelane_b32 v237, s5, 46
	s_add_u32 s4, s84, 0x1aa03500
	s_addc_u32 s5, s85, 0
	v_writelane_b32 v237, s4, 47
	s_cmp_lt_i32 s9, 0
	s_mul_i32 s9, s9, 33
	v_writelane_b32 v237, s5, 48
	s_cselect_b32 s4, s9, s8
	s_add_i32 s4, s4, s7
	s_ashr_i32 s5, s4, 31
	s_lshr_b32 s5, s5, 26
	s_add_i32 s5, s4, s5
	s_and_b32 s7, s5, 0xffc0
	s_sub_i32 s4, s4, s7
	s_bfe_i32 s7, s4, 0x80000
	s_bfe_u32 s7, s7, 0x3000c
	s_add_i32 s7, s4, s7
	s_and_b32 s8, s7, 0xf8
	s_sub_i32 s4, s4, s8
	s_ashr_i32 s5, s5, 6
	s_bfe_i32 s7, s7, 0x80000
	s_lshl_b32 s5, s5, 3
	s_sext_i32_i16 s7, s7
	s_sext_i32_i8 s4, s4
	s_add_i32 s12, s5, s4
	s_ashr_i32 s4, s7, 3
	v_writelane_b32 v237, s4, 49
	s_lshr_b32 s4, s7, 3
	s_bfe_i64 s[4:5], s[4:5], 0x100000
	s_lshl_b64 s[4:5], s[4:5], 20
	v_writelane_b32 v237, s4, 50
	s_mov_b32 s8, s12
	s_ashr_i32 s13, s12, 31
	v_writelane_b32 v237, s5, 51
	s_lshl_b32 s4, s10, 8
	v_writelane_b32 v237, s4, 52
	s_lshl_b32 s4, s16, 7
	v_writelane_b32 v237, s4, 53
	s_lshl_b32 s4, s16, 5
	v_writelane_b32 v237, s4, 54
	v_writelane_b32 v237, s15, 55
	s_add_i32 s4, s29, s15
	v_writelane_b32 v237, s4, 56
	v_writelane_b32 v237, s16, 57
	s_lshl_b32 s4, s16, 8
	s_ashr_i32 s61, s60, 31
	v_writelane_b32 v237, s17, 58
	v_writelane_b32 v237, s4, 59
	s_lshl_b32 s4, s52, 8
	v_writelane_b32 v237, s4, 60
	s_add_i32 s4, s62, s60
	v_writelane_b32 v237, s4, 61
	s_lshl_b32 s4, s52, 6
	v_writelane_b32 v237, s4, 62
	v_writelane_b32 v237, s8, 63
	s_lshl_b64 s[4:5], s[2:3], 14
	s_lshl_b32 s63, s52, 4
	v_writelane_b32 v236, s9, 0
	s_lshl_b64 s[8:9], s[12:13], 20
	v_writelane_b32 v236, s8, 1
	s_lshl_b32 s30, s52, 7
	s_lshl_b32 s35, s52, 5
	v_writelane_b32 v236, s9, 2
	s_lshl_b64 s[8:9], s[96:97], 14
	v_writelane_b32 v236, s8, 3
	s_lshl_b32 s33, s29, 5
	s_lshl_b32 s58, s29, 3
	v_writelane_b32 v236, s9, 4
	s_lshl_b64 s[8:9], s[2:3], 13
	s_or_b32 s4, s4, 16
	s_lshl_b64 s[94:95], s[60:61], 12
	s_lshl_b64 s[98:99], s[60:61], 13
	v_writelane_b32 v236, s8, 5
	s_lshl_b64 s[26:27], s[52:53], 13
	s_mov_b32 s2, s52
	v_writelane_b32 v236, s9, 6
	s_add_u32 s8, s36, s4
	s_addc_u32 s9, s37, s5
	v_writelane_b32 v236, s8, 7
	s_lshl_b64 s[12:13], s[52:53], 14
	s_add_u32 s4, s38, s4
	v_writelane_b32 v236, s9, 8
	v_writelane_b32 v236, s2, 9
	s_movk_i32 s61, 0x1000
	s_nop 0
	v_writelane_b32 v236, s3, 10
	v_writelane_b32 v236, s36, 11
	s_addc_u32 s5, s39, s5
	s_mul_i32 s2, s6, s14
	v_writelane_b32 v236, s37, 12
	v_writelane_b32 v236, s38, 13
	v_writelane_b32 v236, s39, 14
	v_writelane_b32 v236, s40, 15
	v_writelane_b32 v236, s41, 16
	v_writelane_b32 v236, s42, 17
	v_writelane_b32 v236, s43, 18
	v_writelane_b32 v236, s44, 19
	v_writelane_b32 v236, s45, 20
	v_writelane_b32 v236, s46, 21
	v_writelane_b32 v236, s47, 22
	v_writelane_b32 v236, s48, 23
	v_writelane_b32 v236, s49, 24
	v_writelane_b32 v236, s50, 25
	v_writelane_b32 v236, s51, 26
	v_writelane_b32 v236, s4, 27
	s_xor_b64 s[0:1], s[0:1], -1
	s_nop 0
	v_writelane_b32 v236, s5, 28
	v_writelane_b32 v236, s2, 29
	v_writelane_b32 v236, s0, 30
	s_nop 1
	v_writelane_b32 v236, s1, 31
	s_add_i32 s0, 0, 0x14400
	v_writelane_b32 v236, s0, 32
	s_add_i32 s0, 0, 0x18c00
	v_writelane_b32 v236, s0, 33
	s_add_i32 s0, 0, 0x23fc0
	v_writelane_b32 v236, s0, 34
	s_add_i32 s0, 0, 0x23fc4
	v_writelane_b32 v236, s0, 35
	s_mov_b32 s0, s60
	v_writelane_b32 v236, s0, 36
	s_nop 1
	v_writelane_b32 v236, s1, 37
	v_writelane_b32 v236, s58, 38
	v_writelane_b32 v236, s94, 39
	s_nop 1
	v_writelane_b32 v236, s95, 40
	v_writelane_b32 v236, s33, 41
	v_writelane_b32 v236, s35, 42
	s_branch .LBB0_23
